# scan loader/finisher waves at s_setprio 2 for the duration of the chain
# baseline (speedup 1.0000x reference)
; #define LAS __attribute__((address_space(3)))
; #define SCAN_BAR() do { asm volatile("" ::: "memory"); __builtin_amdgcn_s_barrier(); asm volatile("" ::: "memory"); } while (0)
; #define SCAN_ISSUE(n, slot) do { const unsigned char* s_ = src + (size_t)(n) * step_stride; LAS unsigned char* d_ = lds + (slot) * SR_SLOT + p0 * 1024; \
;         _Pragma("unroll") for (int i_ = 0; i_ < 7; ++i_) glds16_asm(s_ + i_ * 1024, d_ + i_ * 1024, true  ); \
;         if (lw < 2) glds16_asm(s_ + 7 * 1024, d_ + 7 * 1024, true); } while (0)
; #define SCAN_ZISSUE(n) do { const unsigned char* z_ = zsrc + (size_t)(n) * 64 * 2048; LAS unsigned char* d_ = lds + ZT_OFF + ((n) & 1) * 8192 + (2 * lw) * 1024; \
;         glds16_asm(z_, d_, false); glds16_asm(z_ + 8 * 2048, d_ + 1024, false); } while (0)
; __device__ __forceinline__ void scan_prompt_wg(const Params& P, LAS unsigned char* lds, int s, int h, int wave, int lane) {
;     constexpr int NST = 128;
;     const unsigned char* ops0 = P.ws + WS_OPS + ((size_t)(s * 128) * 8 + h) * OPS_UNIT;
;     const size_t step_stride = (size_t)8 * OPS_UNIT;
;     ...
;     if (wave >= 4) {
;         const int lw = wave - 4;
;         const int np = (lw < 2) ? 8 : 7, p0 = (lw < 2) ? 8 * lw : 16 + 7 * (lw - 2);
;         const unsigned char* src = ops0 + (size_t)p0 * 1024 + lane * 16;
;     ...
;         const int ftid = lw * 64 + lane, ft = ftid >> 2, fp = ftid & 3;
;         float gg[16];
; #pragma unroll
;         for (int i = 0; i < 16; ++i) gg[i] = P.gdn_g[16 * fp + i];
;         bf16* Mr = (bf16*)(P.ws + WS_MIX) + ((size_t)s * TP + ft) * 1024 + h * 64 + 16 * fp;
;         const unsigned char* zsrc = (const unsigned char*)((const bf16*)(P.ws + WS_Z) + ((size_t)s * TP + 16 * lw + (lane >> 3)) * 1024 + h * 64) + (lane & 7) * 16;
;     ...
; #pragma unroll
;         for (int i = 0; i < 16; ++i) asm volatile("" : "+v"(gg[i]));
;         SCAN_ZISSUE(0);
;         SCAN_ISSUE(0, 0); SCAN_ISSUE(1, 1); SCAN_ISSUE(2, 2);
;         if (lw < 2) asm volatile("s_waitcnt vmcnt(16)" ::: "memory"); else asm volatile("s_waitcnt vmcnt(14)" ::: "memory");
;         SCAN_BAR();
.LBB0_663:
	v_lshl_or_b32 v15, s17, 6, v164
	s_lshl_b32 s10, s18, 1
	v_lshrrev_b32_e32 v26, 2, v15
	v_mov_b32_e32 v27, 0
	s_add_u32 s4, s4, s10
	v_lshl_add_u64 v[30:31], s[14:15], 0, v[26:27]
	s_addc_u32 s5, s5, 0
	v_lshlrev_b64 v[30:31], 11, v[30:31]
	v_lshl_add_u64 v[30:31], s[4:5], 0, v[30:31]
	v_mov_b32_e32 v15, v27
	v_lshlrev_b32_e32 v23, 7, v26
	v_lshlrev_b32_e32 v27, 5, v28
	s_add_i32 s4, 0, 0x22200
	v_bfe_u32 v100, v26, 2, 2
	v_xor_b32_e32 v100, v100, v28
	v_lshl_add_u32 v26, v100, 5, v23
	v_add3_u32 v27, s4, v23, v27
	s_add_u32 s4, s27, s28
	s_addc_u32 s5, s26, 0
	s_add_u32 s4, s4, s12
	s_addc_u32 s5, s5, s13
	v_readlane_b32 s12, v247, 0
	v_readlane_b32 s13, v247, 1
	s_add_u32 s4, s12, s4
	s_addc_u32 s5, s13, s5
	v_lshl_add_u64 v[18:19], s[4:5], 0, v[18:19]
	s_mov_b64 s[4:5], 0x23900000
	v_lshl_add_u64 v[18:19], v[18:19], 0, s[4:5]
	s_add_u32 s4, s16, s14
	s_addc_u32 s5, s15, 0
	v_lshl_add_u64 v[24:25], s[4:5], 0, v[24:25]
	v_lshlrev_b64 v[24:25], 11, v[24:25]
	v_lshl_or_b32 v23, s2, 7, v24
	s_barrier
	v_or_b32_e32 v24, v23, v22
	v_lshlrev_b32_e32 v14, 1, v14
	v_lshl_add_u64 v[22:23], s[12:13], 0, v[24:25]
	s_mov_b64 s[4:5], 0x3620000
	s_mov_b32 s11, 0
	v_lshl_add_u64 v[14:15], v[30:31], 0, v[14:15]
	v_lshl_add_u64 v[22:23], v[22:23], 0, s[4:5]
	s_mov_b32 s2, 3
	s_movk_i32 s43, 0x2000
	s_mov_b32 s10, -1
	s_mov_b32 s44, 0x1e000
	v_mov_b32_e32 v24, 0x358637bd
	s_mov_b64 s[4:5], 0x4000
	s_mov_b64 s[12:13], 0xf0000
	s_mov_b64 s[14:15], 0xf0400
	s_mov_b64 s[16:17], 0xf0800
	s_mov_b64 s[18:19], 0xf0c00
	s_mov_b64 s[24:25], 0xf1000
	s_mov_b64 s[26:27], 0xf1400
	s_mov_b64 s[28:29], 0xf1800
	s_mov_b64 s[30:31], 0xf1c00
	s_mov_b64 s[34:35], 0x50000
	s_mov_b64 s[36:37], 0x20000
	s_setprio 2
	s_branch .LBB0_666

; #define REP(k) _Pragma("unroll") for (int rep_ = 0; rep_ < ((PROBE_REP == (k)) ? 2 : 1); ++rep_)
; __global__ void __launch_bounds__(NWAVES * 64, 2) fwd_kernel(Params P) {
;     ...
;             __syncthreads();
;             REP(30) { scan_prompt_wg(P, lds, (int)blockIdx.x >> 3, (int)blockIdx.x & 7, wave, lane); __syncthreads(); }
;             __syncthreads();
;         }
;         attn_setup(P, lds, tid);
.LBB0_683:
	s_setprio 0
	s_waitcnt lgkmcnt(0)
	s_barrier
	s_barrier
	s_mov_b64 s[6:7], -1
	s_branch .LBB0_746
